# attention tile loop: one static s_setprio 1 for waves 4-7 before the loop, reset after it
# baseline (speedup 1.0000x reference)
.LBB0_1098:
	s_xor_b64 s[30:31], s[0:1], -1
	s_and_b64 s[0:1], s[0:1], exec
	s_cselect_b32 s1, s19, s37
	v_mov_b32_e32 v174, v190
	s_lshl_b32 s14, s1, 15
	s_lshl_b32 s0, s1, 16
	s_add_u32 s4, s16, s0
	v_readfirstlane_b32 s7, v174
	s_addc_u32 s5, s17, 0
	s_ashr_i32 s0, s7, 6
	v_lshlrev_b32_e32 v1, 3, v174
	s_lshl_b32 s6, s1, 8
	s_lshl_b32 s38, s1, 2
	s_ashr_i32 s1, s0, 31
	v_ashrrev_i32_e32 v0, 4, v174
	v_and_b32_e32 v2, 0x78, v1
	v_and_b32_e32 v175, 31, v174
	v_bfe_u32 v176, v174, 5, 1
	s_lshl_b32 s39, s0, 5
	s_and_b32 s7, s7, 0x3fffffc0
	s_lshl_b64 s[28:29], s[0:1], 13
	v_lshlrev_b32_e32 v2, 1, v2
	v_lshlrev_b32_e32 v3, 8, v0
	v_lshlrev_b32_e32 v10, 8, v175
	v_lshlrev_b32_e32 v11, 4, v176
	s_add_u32 s0, s4, s28
	v_or_b32_e32 v148, v2, v3
	v_or_b32_e32 v12, v11, v10
	s_addc_u32 s1, s5, s29
	global_load_dwordx4 v[96:99], v148, s[22:23]
	global_load_dwordx4 v[100:103], v148, s[20:21]
	global_load_dwordx4 v[136:139], v148, s[42:43]
	global_load_dwordx4 v[140:143], v148, s[26:27]
	global_load_dwordx4 v[104:107], v12, s[0:1]
	global_load_dwordx4 v[108:111], v12, s[0:1] offset:32
	global_load_dwordx4 v[112:115], v12, s[0:1] offset:64
	global_load_dwordx4 v[116:119], v12, s[0:1] offset:96
	global_load_dwordx4 v[120:123], v12, s[0:1] offset:128
	global_load_dwordx4 v[124:127], v12, s[0:1] offset:160
	global_load_dwordx4 v[128:131], v12, s[0:1] offset:192
	global_load_dwordx4 v[132:135], v12, s[0:1] offset:224
	v_and_b32_e32 v6, 0xfffff0, v0
	v_lshlrev_b32_e32 v7, 1, v0
	v_and_or_b32 v6, v7, 8, v6
	v_lshrrev_b32_e32 v7, 1, v0
	v_and_b32_e32 v8, 3, v0
	v_add_u32_e32 v0, 32, v0
	v_and_b32_e32 v4, 63, v174
	v_and_b32_e32 v9, 0xfffff0, v0
	v_lshlrev_b32_e32 v0, 1, v0
	v_lshlrev_b32_e32 v12, 4, v174
	s_lshl_b32 s0, s7, 2
	v_and_or_b32 v0, v0, 8, v9
	v_lshlrev_b32_e32 v9, 3, v4
	v_and_b32_e32 v13, 0xc0, v12
	v_lshlrev_b32_e32 v14, 1, v174
	s_add_i32 s0, s0, 0
	v_lshlrev_b32_e32 v5, 2, v176
	v_and_or_b32 v13, v9, 24, v13
	v_and_b32_e32 v14, 32, v14
	v_and_b32_e32 v9, 0x100, v9
	s_add_i32 s18, s38, 4
	s_add_i32 s39, s39, s6
	s_add_i32 s4, s0, 0x10000
	v_lshrrev_b32_e32 v6, 1, v6
	v_bfe_u32 v1, v1, 5, 2
	v_lshrrev_b32_e32 v0, 1, v0
	v_or3_b32 v9, v13, v14, v9
	v_subrev_u32_e32 v13, s6, v5
	s_cmp_lg_u32 0, -1
	v_or_b32_e32 v6, v6, v1
	v_and_or_b32 v7, v7, 4, v8
	v_or_b32_e32 v0, v0, v1
	v_and_b32_e32 v1, 0x70, v174
	v_cvt_f32_i32_e32 v13, v13
	s_cselect_b32 s0, 0, 0
	v_lshlrev_b32_e32 v6, 9, v6
	v_lshlrev_b32_e32 v7, 6, v7
	v_and_b32_e32 v8, 48, v2
	v_lshlrev_b32_e32 v0, 9, v0
	v_bitop3_b32 v1, v2, v3, v1 bitop3:0xde
	v_add_u32_e32 v178, s0, v9
	s_movk_i32 s0, 0x70
	v_or3_b32 v0, v0, v7, v8
	v_or3_b32 v6, v6, v7, v8
	v_add_u32_e32 v182, 0, v1
	v_bfe_u32 v200, v174, 7, 1
	v_lshlrev_b32_e32 v200, 7, v200
	v_xor_b32_e32 v182, v182, v200
	v_and_b32_e32 v1, 0x70, v12
	v_bitop3_b32 v2, v11, v12, s0 bitop3:0x78
	s_movk_i32 s0, 0x60
	s_waitcnt vmcnt(0)
	v_add_u32_e32 v180, 0, v6
	v_add_u32_e32 v181, 0, v0
	v_add_u32_e32 v0, 0, v10
	v_bitop3_b32 v3, v11, v1, 32 bitop3:0x36
	v_bitop3_b32 v6, v11, v1, 64 bitop3:0x36
	v_bitop3_b32 v1, v11, v1, s0 bitop3:0x36
	v_cmp_gt_u32_e64 s[0:1], 32, v4
	v_or_b32_e32 v4, s39, v175
	v_mov_b32_e32 v32, v149
	v_mov_b32_e32 v33, v149
	v_mov_b32_e32 v46, v149
	v_mov_b32_e32 v47, v149
	v_mul_f32_e32 v179, v172, v13
	v_add_u32_e32 v177, s4, v11
	v_sub_u32_e32 v184, v4, v5
	v_mov_b32_e32 v34, v149
	v_mov_b32_e32 v35, v149
	v_mov_b32_e32 v36, v149
	v_mov_b32_e32 v37, v149
	v_mov_b32_e32 v38, v149
	v_mov_b32_e32 v39, v149
	v_mov_b32_e32 v40, v149
	v_mov_b32_e32 v41, v149
	v_mov_b32_e32 v42, v149
	v_mov_b32_e32 v43, v149
	v_mov_b32_e32 v44, v149
	v_mov_b32_e32 v45, v149
	v_add_u32_e32 v186, v0, v2
	v_add_u32_e32 v187, v0, v3
	v_add_u32_e32 v188, v0, v6
	v_add_u32_e32 v189, v0, v1
	v_bfe_u32 v200, v174, 3, 1
	v_lshlrev_b32_e32 v200, 7, v200
	v_xor_b32_e32 v186, v186, v200
	v_xor_b32_e32 v187, v187, v200
	v_xor_b32_e32 v188, v188, v200
	v_xor_b32_e32 v189, v189, v200
	v_mov_b64_e32 v[62:63], v[46:47]
	v_mov_b64_e32 v[16:17], v[32:33]
	v_mov_b64_e32 v[0:1], v[32:33]
	s_mov_b32 s12, 0
	v_lshl_add_u32 v183, v175, 2, s4
	v_mov_b32_e32 v203, 0xf149f2ca
	v_mov_b32_e32 v185, 0
	s_movk_i32 s13, 0x7f
	s_mov_b64 s[46:47], s[2:3]
	s_mov_b64 s[40:41], s[24:25]
	v_mov_b64_e32 v[60:61], v[44:45]
	v_mov_b64_e32 v[58:59], v[42:43]
	v_mov_b64_e32 v[56:57], v[40:41]
	v_mov_b64_e32 v[54:55], v[38:39]
	v_mov_b64_e32 v[52:53], v[36:37]
	v_mov_b64_e32 v[50:51], v[34:35]
	v_mov_b64_e32 v[48:49], v[32:33]
	v_mov_b64_e32 v[18:19], v[34:35]
	v_mov_b64_e32 v[20:21], v[36:37]
	v_mov_b64_e32 v[22:23], v[38:39]
	v_mov_b64_e32 v[24:25], v[40:41]
	v_mov_b64_e32 v[26:27], v[42:43]
	v_mov_b64_e32 v[28:29], v[44:45]
	v_mov_b64_e32 v[30:31], v[46:47]
	v_mov_b64_e32 v[2:3], v[34:35]
	v_mov_b64_e32 v[4:5], v[36:37]
	v_mov_b64_e32 v[6:7], v[38:39]
	v_mov_b64_e32 v[8:9], v[40:41]
	v_mov_b64_e32 v[10:11], v[42:43]
	v_mov_b64_e32 v[12:13], v[44:45]
	v_mov_b64_e32 v[14:15], v[46:47]
	s_waitcnt vmcnt(11)
	ds_write_b128 v180, v[96:99]
	s_waitcnt vmcnt(10)
	ds_write_b128 v181, v[100:103]
	s_waitcnt vmcnt(9)
	ds_write_b128 v182, v[136:139] offset:32768
	s_waitcnt vmcnt(8)
	ds_write_b128 v182, v[140:143] offset:40960
	s_waitcnt lgkmcnt(0)
	s_barrier
	v_add_u32_e32 v168, 0x4000, v148
	global_load_dwordx4 v[136:139], v168, s[42:43]
	global_load_dwordx4 v[140:143], v168, s[26:27]
	v_add_u32_e32 v169, 0x4000, v168
	s_mov_b32 s13, 0
	s_mov_b32 s12, 0
	s_mov_b32 s10, 0x3e0293ee
	s_mov_b32 s6, 0x11000
	s_mov_b32 s7, 0
	s_mov_b32 s8, 0x4000
	ds_read_b128 v[236:239], v186 offset:32768
	ds_read_b128 v[240:243], v186 offset:40960
	v_mov_b32_e32 v244, 0
	v_mov_b32_e32 v245, 0
	v_mov_b32_e32 v246, 0
	v_mov_b32_e32 v247, 0
	v_add_u32_e32 v200, s6, v180
	v_add_u32_e32 v201, s6, v181
	ds_write_b128 v200, v[244:247]
	ds_write_b128 v201, v[244:247]
	v_mov_b32_e32 v204, 0
	v_mov_b32_e32 v205, 0
	v_mov_b32_e32 v206, 0
	v_mov_b32_e32 v207, 0
	v_mov_b32_e32 v208, 0
	v_mov_b32_e32 v209, 0
	v_mov_b32_e32 v210, 0
	v_mov_b32_e32 v211, 0
	v_mov_b32_e32 v212, 0
	v_mov_b32_e32 v213, 0
	v_mov_b32_e32 v214, 0
	v_mov_b32_e32 v215, 0
	v_mov_b32_e32 v216, 0
	v_mov_b32_e32 v217, 0
	v_mov_b32_e32 v218, 0
	v_mov_b32_e32 v219, 0
	v_cvt_f32_u32_e32 v64, s13
	v_mov_b32_e32 v165, v164
	v_fma_f32 v64, v172, v64, v179
	v_add_f32_e32 v68, v173, v64
	v_add_f32_e32 v72, v173, v68
	v_add_f32_e32 v76, v173, v72
	v_add_f32_e32 v65, v172, v64
	v_add_f32_e32 v69, v172, v68
	v_add_f32_e32 v73, v172, v72
	v_add_f32_e32 v77, v172, v76
	v_pk_add_f32 v[66:67], v[162:163], v[64:65] op_sel_hi:[1,0]
	v_pk_add_f32 v[70:71], v[162:163], v[68:69] op_sel_hi:[1,0]
	v_pk_add_f32 v[74:75], v[162:163], v[72:73] op_sel_hi:[1,0]
	v_pk_add_f32 v[78:79], v[162:163], v[76:77] op_sel_hi:[1,0]
	v_pk_add_f32 v[82:83], v[164:165], v[66:67]
	v_pk_add_f32 v[80:81], v[166:167], v[64:65]
	v_pk_add_f32 v[86:87], v[164:165], v[70:71]
	v_pk_add_f32 v[84:85], v[164:165], v[68:69]
	v_pk_add_f32 v[90:91], v[164:165], v[74:75]
	v_pk_add_f32 v[88:89], v[164:165], v[72:73]
	v_pk_add_f32 v[94:95], v[164:165], v[78:79]
	v_pk_add_f32 v[92:93], v[164:165], v[76:77]
	s_addk_i32 s13, 0x40
	s_waitcnt lgkmcnt(3)
	v_mfma_f32_32x32x16_bf16 v[64:79], v[236:239], v[104:107], v[64:79]
	ds_read_b128 v[236:239], v187 offset:32768
	s_waitcnt lgkmcnt(3)
	v_mfma_f32_32x32x16_bf16 v[80:95], v[240:243], v[104:107], v[80:95]
	ds_read_b128 v[240:243], v187 offset:40960
	s_waitcnt lgkmcnt(1)
	v_mfma_f32_32x32x16_bf16 v[64:79], v[236:239], v[108:111], v[64:79]
	ds_read_b128 v[236:239], v188 offset:32768
	s_waitcnt lgkmcnt(1)
	v_mfma_f32_32x32x16_bf16 v[80:95], v[240:243], v[108:111], v[80:95]
	ds_read_b128 v[240:243], v188 offset:40960
	s_waitcnt lgkmcnt(1)
	v_mfma_f32_32x32x16_bf16 v[64:79], v[236:239], v[112:115], v[64:79]
	ds_read_b128 v[236:239], v189 offset:32768
	s_waitcnt lgkmcnt(1)
	v_mfma_f32_32x32x16_bf16 v[80:95], v[240:243], v[112:115], v[80:95]
	ds_read_b128 v[240:243], v189 offset:40960
	s_waitcnt lgkmcnt(1)
	v_mfma_f32_32x32x16_bf16 v[64:79], v[236:239], v[116:119], v[64:79]
	v_xor_b32_e32 v186, 0x80, v186
	v_xor_b32_e32 v187, 0x80, v187
	v_xor_b32_e32 v188, 0x80, v188
	v_xor_b32_e32 v189, 0x80, v189
	ds_read_b128 v[236:239], v186 offset:32768
	s_waitcnt lgkmcnt(1)
	v_mfma_f32_32x32x16_bf16 v[80:95], v[240:243], v[116:119], v[80:95]
	ds_read_b128 v[240:243], v186 offset:40960
	s_waitcnt lgkmcnt(1)
	v_mfma_f32_32x32x16_bf16 v[64:79], v[236:239], v[120:123], v[64:79]
	ds_read_b128 v[236:239], v187 offset:32768
	s_waitcnt lgkmcnt(1)
	v_mfma_f32_32x32x16_bf16 v[80:95], v[240:243], v[120:123], v[80:95]
	ds_read_b128 v[240:243], v187 offset:40960
	s_waitcnt lgkmcnt(1)
	v_mfma_f32_32x32x16_bf16 v[64:79], v[236:239], v[124:127], v[64:79]
	ds_read_b128 v[236:239], v188 offset:32768
	s_waitcnt lgkmcnt(1)
	v_mfma_f32_32x32x16_bf16 v[80:95], v[240:243], v[124:127], v[80:95]
	ds_read_b128 v[240:243], v188 offset:40960
	s_waitcnt lgkmcnt(1)
	v_mfma_f32_32x32x16_bf16 v[64:79], v[236:239], v[128:131], v[64:79]
	ds_read_b128 v[236:239], v189 offset:32768
	s_waitcnt lgkmcnt(1)
	v_mfma_f32_32x32x16_bf16 v[80:95], v[240:243], v[128:131], v[80:95]
	ds_read_b128 v[240:243], v189 offset:40960
	s_waitcnt lgkmcnt(1)
	v_mfma_f32_32x32x16_bf16 v[64:79], v[236:239], v[132:135], v[64:79]
	s_waitcnt lgkmcnt(0)
	v_mfma_f32_32x32x16_bf16 v[80:95], v[240:243], v[132:135], v[80:95]
	s_waitcnt vmcnt(0)
	ds_write_b128 v182, v[136:139] offset:49152
	ds_write_b128 v182, v[140:143] offset:57344
	s_waitcnt lgkmcnt(0)
	s_barrier
	v_readfirstlane_b32 s4, v190
	s_nop 3
	s_lshr_b32 s4, s4, 6
	s_cmp_ge_u32 s4, 4
	s_cbranch_scc0 .Lat_prio
	s_setprio 1
.Lat_prio:
	.p2alignl 6, 3212836864

.Lat_nwo:
	s_mov_b32 s9, s6
	s_mov_b32 s6, s7
	s_mov_b32 s7, s8
	s_mov_b32 s8, s9
	s_add_i32 s12, s12, 2
	s_cmp_lt_u32 s12, s18
	s_cbranch_scc1 .Lat_loop
	s_setprio 0
	v_add_u32_e32 v165, s6, v178
	ds_read_b64_tr_b16 v[220:221], v165 offset:0
	ds_read_b64_tr_b16 v[222:223], v165 offset:2048
	ds_read_b64_tr_b16 v[224:225], v165 offset:4096
	ds_read_b64_tr_b16 v[226:227], v165 offset:6144
	ds_read_b64_tr_b16 v[228:229], v165 offset:8192
	ds_read_b64_tr_b16 v[230:231], v165 offset:10240
	ds_read_b64_tr_b16 v[232:233], v165 offset:12288
	ds_read_b64_tr_b16 v[234:235], v165 offset:14336
	s_waitcnt lgkmcnt(6)
	v_mfma_f32_32x32x16_bf16 v[32:47], v[204:207], v[220:223], v[32:47]
	ds_read_b64_tr_b16 v[220:221], v165 offset:512
	ds_read_b64_tr_b16 v[222:223], v165 offset:2560
	s_waitcnt lgkmcnt(6)
	v_mfma_f32_32x32x16_bf16 v[32:47], v[208:211], v[224:227], v[32:47]
	ds_read_b64_tr_b16 v[224:225], v165 offset:4608
	ds_read_b64_tr_b16 v[226:227], v165 offset:6656
	s_waitcnt lgkmcnt(6)
	v_mfma_f32_32x32x16_bf16 v[32:47], v[212:215], v[228:231], v[32:47]
	ds_read_b64_tr_b16 v[228:229], v165 offset:8704
	ds_read_b64_tr_b16 v[230:231], v165 offset:10752
	s_waitcnt lgkmcnt(6)
	v_mfma_f32_32x32x16_bf16 v[32:47], v[216:219], v[232:235], v[32:47]
	ds_read_b64_tr_b16 v[232:233], v165 offset:12800
	ds_read_b64_tr_b16 v[234:235], v165 offset:14848
	s_waitcnt lgkmcnt(6)
	v_mfma_f32_32x32x16_bf16 v[48:63], v[204:207], v[220:223], v[48:63]
	ds_read_b64_tr_b16 v[220:221], v165 offset:1024
	ds_read_b64_tr_b16 v[222:223], v165 offset:3072
	s_waitcnt lgkmcnt(6)
	v_mfma_f32_32x32x16_bf16 v[48:63], v[208:211], v[224:227], v[48:63]
	ds_read_b64_tr_b16 v[224:225], v165 offset:5120
	ds_read_b64_tr_b16 v[226:227], v165 offset:7168
	s_waitcnt lgkmcnt(6)
	v_mfma_f32_32x32x16_bf16 v[48:63], v[212:215], v[228:231], v[48:63]
	ds_read_b64_tr_b16 v[228:229], v165 offset:9216
	ds_read_b64_tr_b16 v[230:231], v165 offset:11264
	s_waitcnt lgkmcnt(6)
	v_mfma_f32_32x32x16_bf16 v[48:63], v[216:219], v[232:235], v[48:63]
	ds_read_b64_tr_b16 v[232:233], v165 offset:13312
	ds_read_b64_tr_b16 v[234:235], v165 offset:15360
	s_waitcnt lgkmcnt(6)
	v_mfma_f32_32x32x16_bf16 v[16:31], v[204:207], v[220:223], v[16:31]
	ds_read_b64_tr_b16 v[220:221], v165 offset:1536
	ds_read_b64_tr_b16 v[222:223], v165 offset:3584
	s_waitcnt lgkmcnt(6)
	v_mfma_f32_32x32x16_bf16 v[16:31], v[208:211], v[224:227], v[16:31]
	ds_read_b64_tr_b16 v[224:225], v165 offset:5632
	ds_read_b64_tr_b16 v[226:227], v165 offset:7680
	s_waitcnt lgkmcnt(6)
	v_mfma_f32_32x32x16_bf16 v[16:31], v[212:215], v[228:231], v[16:31]
	ds_read_b64_tr_b16 v[228:229], v165 offset:9728
	ds_read_b64_tr_b16 v[230:231], v165 offset:11776
	s_waitcnt lgkmcnt(6)
	v_mfma_f32_32x32x16_bf16 v[16:31], v[216:219], v[232:235], v[16:31]
	ds_read_b64_tr_b16 v[232:233], v165 offset:13824
	ds_read_b64_tr_b16 v[234:235], v165 offset:15872
	s_waitcnt lgkmcnt(6)
	v_mfma_f32_32x32x16_bf16 v[0:15], v[204:207], v[220:223], v[0:15]
	s_waitcnt lgkmcnt(4)
	v_mfma_f32_32x32x16_bf16 v[0:15], v[208:211], v[224:227], v[0:15]
	s_waitcnt lgkmcnt(2)
	v_mfma_f32_32x32x16_bf16 v[0:15], v[212:215], v[228:231], v[0:15]
	s_waitcnt lgkmcnt(0)
	v_mfma_f32_32x32x16_bf16 v[0:15], v[216:219], v[232:235], v[0:15]
	s_nop 7
	s_nop 7
